# attention steps: mid-step full vmcnt drains in front of the V reads removed; step-closing wait counted so the DMA two steps ahead stays in flight across the barrier
# speedup vs baseline: 1.0047x; 1.0046x over previous
.LBB0_769:
	v_add3_u32 v0, s2, v190, v188
	v_cmp_neq_f32_e32 vcc, s54, v208
	v_add3_u32 v3, v0, v189, s81
	v_add_u32_e32 v0, s2, v191
	v_mov_b32_e32 v4, 0
	v_cndmask_b32_e32 v2, 0, v208, vcc
	v_add3_u32 v0, v0, v189, s81
	s_and_b64 vcc, exec, s[38:39]
	s_cbranch_vccnz .LBB0_777
	v_sub_f32_e32 v8, v112, v2
	v_exp_f32_e32 v12, v8
	v_sub_f32_e32 v8, v113, v2
	v_exp_f32_e32 v13, v8
	v_sub_f32_e32 v8, v114, v2
	v_exp_f32_e32 v14, v8
	v_sub_f32_e32 v8, v115, v2
	v_exp_f32_e32 v15, v8
	v_sub_f32_e32 v8, v116, v2
	v_exp_f32_e32 v17, v8
	v_sub_f32_e32 v8, v117, v2
	v_exp_f32_e32 v18, v8
	v_sub_f32_e32 v8, v118, v2
	v_exp_f32_e32 v19, v8
	v_sub_f32_e32 v8, v119, v2
	s_nop 0
	ds_read_b64_tr_b16 v[4:5], v3
	ds_read_b64_tr_b16 v[6:7], v3 offset:1024
	v_exp_f32_e32 v20, v8
	v_cvt_pk_bf16_f32 v8, v12, v13
	v_cvt_pk_bf16_f32 v9, v14, v15
	v_cvt_pk_bf16_f32 v10, v17, v18
	v_cvt_pk_bf16_f32 v11, v19, v20
	s_waitcnt lgkmcnt(0)
	s_nop 0
	v_mfma_f32_32x32x16_bf16 v[48:63], v[4:7], v[8:11], v[48:63]
	ds_read_b64_tr_b16 v[4:5], v0
	ds_read_b64_tr_b16 v[6:7], v0 offset:1024
	s_waitcnt lgkmcnt(0)
	v_mfma_f32_32x32x16_bf16 v[32:47], v[4:7], v[8:11], v[32:47]
	v_add_f32_e32 v4, 0, v12
	v_add_f32_e32 v4, v13, v4
	v_add_f32_e32 v4, v14, v4
	v_add_f32_e32 v4, v15, v4
	v_add_f32_e32 v4, v17, v4
	v_add_f32_e32 v4, v18, v4
	v_add_f32_e32 v4, v19, v4
	v_add_f32_e32 v4, v20, v4
	s_and_b64 vcc, exec, s[38:39]
	s_cbranch_vccz .LBB0_778

.LBB0_772:
	v_sub_f32_e32 v10, v97, v2
	v_exp_f32_e32 v14, v10
	v_sub_f32_e32 v10, v98, v2
	v_exp_f32_e32 v15, v10
	v_sub_f32_e32 v10, v99, v2
	v_exp_f32_e32 v17, v10
	v_sub_f32_e32 v10, v100, v2
	v_exp_f32_e32 v18, v10
	v_sub_f32_e32 v10, v101, v2
	v_exp_f32_e32 v19, v10
	v_sub_f32_e32 v10, v102, v2
	v_sub_f32_e32 v5, v96, v2
	v_exp_f32_e32 v20, v10
	v_sub_f32_e32 v10, v103, v2
	s_nop 0
	ds_read_b64_tr_b16 v[6:7], v3 offset:4096
	ds_read_b64_tr_b16 v[8:9], v3 offset:5120
	v_exp_f32_e32 v5, v5
	v_exp_f32_e32 v21, v10
	v_cvt_pk_bf16_f32 v11, v15, v17
	v_cvt_pk_bf16_f32 v12, v18, v19
	v_cvt_pk_bf16_f32 v10, v5, v14
	v_cvt_pk_bf16_f32 v13, v20, v21
	v_add_f32_e32 v4, v5, v4
	v_add_f32_e32 v4, v14, v4
	s_waitcnt lgkmcnt(0)
	v_mfma_f32_32x32x16_bf16 v[48:63], v[6:9], v[10:13], v[48:63]
	ds_read_b64_tr_b16 v[6:7], v0 offset:4096
	ds_read_b64_tr_b16 v[8:9], v0 offset:5120
	v_add_f32_e32 v4, v15, v4
	v_add_f32_e32 v4, v17, v4
	v_add_f32_e32 v4, v18, v4
	v_add_f32_e32 v4, v19, v4
	v_add_f32_e32 v4, v20, v4
	v_add_f32_e32 v4, v21, v4
	s_waitcnt lgkmcnt(0)
	v_mfma_f32_32x32x16_bf16 v[32:47], v[6:9], v[10:13], v[32:47]
	s_and_b64 vcc, exec, s[38:39]
	s_cbranch_vccz .LBB0_780

.LBB0_774:
	v_sub_f32_e32 v10, v81, v2
	v_exp_f32_e32 v14, v10
	v_sub_f32_e32 v10, v82, v2
	v_exp_f32_e32 v15, v10
	v_sub_f32_e32 v10, v83, v2
	v_exp_f32_e32 v17, v10
	v_sub_f32_e32 v10, v84, v2
	v_exp_f32_e32 v18, v10
	v_sub_f32_e32 v10, v85, v2
	v_exp_f32_e32 v19, v10
	v_sub_f32_e32 v10, v86, v2
	v_sub_f32_e32 v5, v80, v2
	v_exp_f32_e32 v20, v10
	v_sub_f32_e32 v10, v87, v2
	s_nop 0
	ds_read_b64_tr_b16 v[6:7], v3 offset:8192
	ds_read_b64_tr_b16 v[8:9], v3 offset:9216
	v_exp_f32_e32 v5, v5
	v_exp_f32_e32 v21, v10
	v_cvt_pk_bf16_f32 v11, v15, v17
	v_cvt_pk_bf16_f32 v12, v18, v19
	v_cvt_pk_bf16_f32 v10, v5, v14
	v_cvt_pk_bf16_f32 v13, v20, v21
	v_add_f32_e32 v4, v5, v4
	v_add_f32_e32 v4, v14, v4
	s_waitcnt lgkmcnt(0)
	v_mfma_f32_32x32x16_bf16 v[48:63], v[6:9], v[10:13], v[48:63]
	ds_read_b64_tr_b16 v[6:7], v0 offset:8192
	ds_read_b64_tr_b16 v[8:9], v0 offset:9216
	v_add_f32_e32 v4, v15, v4
	v_add_f32_e32 v4, v17, v4
	v_add_f32_e32 v4, v18, v4
	v_add_f32_e32 v4, v19, v4
	v_add_f32_e32 v4, v20, v4
	v_add_f32_e32 v4, v21, v4
	s_waitcnt lgkmcnt(0)
	v_mfma_f32_32x32x16_bf16 v[32:47], v[6:9], v[10:13], v[32:47]
	s_and_b64 vcc, exec, s[36:37]
	s_cbranch_vccz .LBB0_782

.LBB0_776:
	v_sub_f32_e32 v10, v65, v2
	v_exp_f32_e32 v14, v10
	v_sub_f32_e32 v10, v66, v2
	v_exp_f32_e32 v15, v10
	v_sub_f32_e32 v10, v67, v2
	v_exp_f32_e32 v17, v10
	v_sub_f32_e32 v10, v68, v2
	v_exp_f32_e32 v18, v10
	v_sub_f32_e32 v10, v69, v2
	v_exp_f32_e32 v19, v10
	v_sub_f32_e32 v10, v70, v2
	v_sub_f32_e32 v5, v64, v2
	v_exp_f32_e32 v20, v10
	v_sub_f32_e32 v10, v71, v2
	s_nop 0
	ds_read_b64_tr_b16 v[6:7], v3 offset:12288
	ds_read_b64_tr_b16 v[8:9], v3 offset:13312
	v_exp_f32_e32 v5, v5
	v_exp_f32_e32 v21, v10
	v_cvt_pk_bf16_f32 v11, v15, v17
	v_cvt_pk_bf16_f32 v12, v18, v19
	v_cvt_pk_bf16_f32 v10, v5, v14
	v_cvt_pk_bf16_f32 v13, v20, v21
	v_add_f32_e32 v4, v5, v4
	v_add_f32_e32 v4, v14, v4
	s_waitcnt lgkmcnt(0)
	v_mfma_f32_32x32x16_bf16 v[48:63], v[6:9], v[10:13], v[48:63]
	ds_read_b64_tr_b16 v[6:7], v0 offset:12288
	ds_read_b64_tr_b16 v[8:9], v0 offset:13312
	v_add_f32_e32 v4, v15, v4
	v_add_f32_e32 v4, v17, v4
	v_add_f32_e32 v4, v18, v4
	v_add_f32_e32 v4, v19, v4
	v_add_f32_e32 v4, v20, v4
	v_add_f32_e32 v4, v21, v4
	s_waitcnt lgkmcnt(0)
	v_mfma_f32_32x32x16_bf16 v[32:47], v[6:9], v[10:13], v[32:47]
	s_and_b64 vcc, exec, s[36:37]
	s_cbranch_vccz .LBB0_784
	s_branch .LBB0_785

.LBB0_778:
	v_sub_f32_e32 v10, v121, v2
	v_exp_f32_e32 v14, v10
	v_sub_f32_e32 v10, v122, v2
	v_exp_f32_e32 v15, v10
	v_sub_f32_e32 v10, v123, v2
	v_exp_f32_e32 v17, v10
	v_sub_f32_e32 v10, v124, v2
	v_exp_f32_e32 v18, v10
	v_sub_f32_e32 v10, v125, v2
	v_exp_f32_e32 v19, v10
	v_sub_f32_e32 v10, v126, v2
	v_sub_f32_e32 v5, v120, v2
	v_exp_f32_e32 v20, v10
	v_sub_f32_e32 v10, v127, v2
	s_nop 0
	ds_read_b64_tr_b16 v[6:7], v3 offset:2048
	ds_read_b64_tr_b16 v[8:9], v3 offset:3072
	v_exp_f32_e32 v5, v5
	v_exp_f32_e32 v21, v10
	v_cvt_pk_bf16_f32 v11, v15, v17
	v_cvt_pk_bf16_f32 v12, v18, v19
	v_cvt_pk_bf16_f32 v10, v5, v14
	v_cvt_pk_bf16_f32 v13, v20, v21
	v_add_f32_e32 v4, v5, v4
	v_add_f32_e32 v4, v14, v4
	s_waitcnt lgkmcnt(0)
	v_mfma_f32_32x32x16_bf16 v[48:63], v[6:9], v[10:13], v[48:63]
	ds_read_b64_tr_b16 v[6:7], v0 offset:2048
	ds_read_b64_tr_b16 v[8:9], v0 offset:3072
	v_add_f32_e32 v4, v15, v4
	v_add_f32_e32 v4, v17, v4
	v_add_f32_e32 v4, v18, v4
	v_add_f32_e32 v4, v19, v4
	v_add_f32_e32 v4, v20, v4
	v_add_f32_e32 v4, v21, v4
	s_waitcnt lgkmcnt(0)
	v_mfma_f32_32x32x16_bf16 v[32:47], v[6:9], v[10:13], v[32:47]
	s_and_b64 vcc, exec, s[38:39]
	s_cbranch_vccz .LBB0_772

.LBB0_780:
	v_sub_f32_e32 v10, v105, v2
	v_exp_f32_e32 v14, v10
	v_sub_f32_e32 v10, v106, v2
	v_exp_f32_e32 v15, v10
	v_sub_f32_e32 v10, v107, v2
	v_exp_f32_e32 v17, v10
	v_sub_f32_e32 v10, v108, v2
	v_exp_f32_e32 v18, v10
	v_sub_f32_e32 v10, v109, v2
	v_exp_f32_e32 v19, v10
	v_sub_f32_e32 v10, v110, v2
	v_sub_f32_e32 v5, v104, v2
	v_exp_f32_e32 v20, v10
	v_sub_f32_e32 v10, v111, v2
	s_nop 0
	ds_read_b64_tr_b16 v[6:7], v3 offset:6144
	ds_read_b64_tr_b16 v[8:9], v3 offset:7168
	v_exp_f32_e32 v5, v5
	v_exp_f32_e32 v21, v10
	v_cvt_pk_bf16_f32 v11, v15, v17
	v_cvt_pk_bf16_f32 v12, v18, v19
	v_cvt_pk_bf16_f32 v10, v5, v14
	v_cvt_pk_bf16_f32 v13, v20, v21
	v_add_f32_e32 v4, v5, v4
	v_add_f32_e32 v4, v14, v4
	s_waitcnt lgkmcnt(0)
	v_mfma_f32_32x32x16_bf16 v[48:63], v[6:9], v[10:13], v[48:63]
	ds_read_b64_tr_b16 v[6:7], v0 offset:6144
	ds_read_b64_tr_b16 v[8:9], v0 offset:7168
	v_add_f32_e32 v4, v15, v4
	v_add_f32_e32 v4, v17, v4
	v_add_f32_e32 v4, v18, v4
	v_add_f32_e32 v4, v19, v4
	v_add_f32_e32 v4, v20, v4
	v_add_f32_e32 v4, v21, v4
	s_waitcnt lgkmcnt(0)
	v_mfma_f32_32x32x16_bf16 v[32:47], v[6:9], v[10:13], v[32:47]
	s_and_b64 vcc, exec, s[36:37]
	s_cbranch_vccz .LBB0_774

.LBB0_782:
	v_sub_f32_e32 v10, v89, v2
	v_exp_f32_e32 v14, v10
	v_sub_f32_e32 v10, v90, v2
	v_exp_f32_e32 v15, v10
	v_sub_f32_e32 v10, v91, v2
	v_exp_f32_e32 v17, v10
	v_sub_f32_e32 v10, v92, v2
	v_exp_f32_e32 v18, v10
	v_sub_f32_e32 v10, v93, v2
	v_exp_f32_e32 v19, v10
	v_sub_f32_e32 v10, v94, v2
	v_sub_f32_e32 v5, v88, v2
	v_exp_f32_e32 v20, v10
	v_sub_f32_e32 v10, v95, v2
	s_nop 0
	ds_read_b64_tr_b16 v[6:7], v3 offset:10240
	ds_read_b64_tr_b16 v[8:9], v3 offset:11264
	v_exp_f32_e32 v5, v5
	v_exp_f32_e32 v21, v10
	v_cvt_pk_bf16_f32 v11, v15, v17
	v_cvt_pk_bf16_f32 v12, v18, v19
	v_cvt_pk_bf16_f32 v10, v5, v14
	v_cvt_pk_bf16_f32 v13, v20, v21
	v_add_f32_e32 v4, v5, v4
	v_add_f32_e32 v4, v14, v4
	s_waitcnt lgkmcnt(0)
	v_mfma_f32_32x32x16_bf16 v[48:63], v[6:9], v[10:13], v[48:63]
	ds_read_b64_tr_b16 v[6:7], v0 offset:10240
	ds_read_b64_tr_b16 v[8:9], v0 offset:11264
	v_add_f32_e32 v4, v15, v4
	v_add_f32_e32 v4, v17, v4
	v_add_f32_e32 v4, v18, v4
	v_add_f32_e32 v4, v19, v4
	v_add_f32_e32 v4, v20, v4
	v_add_f32_e32 v4, v21, v4
	s_waitcnt lgkmcnt(0)
	v_mfma_f32_32x32x16_bf16 v[32:47], v[6:9], v[10:13], v[32:47]
	s_and_b64 vcc, exec, s[36:37]
	s_cbranch_vccz .LBB0_776

.LBB0_784:
	v_sub_f32_e32 v10, v74, v2
	v_exp_f32_e32 v14, v10
	v_sub_f32_e32 v10, v75, v2
	v_exp_f32_e32 v15, v10
	v_sub_f32_e32 v10, v76, v2
	v_exp_f32_e32 v17, v10
	v_sub_f32_e32 v10, v77, v2
	s_nop 0
	ds_read_b64_tr_b16 v[6:7], v3 offset:14336
	ds_read_b64_tr_b16 v[8:9], v3 offset:15360
	v_sub_f32_e32 v3, v72, v2
	v_sub_f32_e32 v5, v73, v2
	v_exp_f32_e32 v18, v10
	v_sub_f32_e32 v10, v78, v2
	v_sub_f32_e32 v2, v79, v2
	v_exp_f32_e32 v3, v3
	v_exp_f32_e32 v5, v5
	v_exp_f32_e32 v19, v10
	v_exp_f32_e32 v2, v2
	v_cvt_pk_bf16_f32 v11, v14, v15
	v_cvt_pk_bf16_f32 v10, v3, v5
	v_cvt_pk_bf16_f32 v12, v17, v18
	v_cvt_pk_bf16_f32 v13, v19, v2
	s_waitcnt lgkmcnt(0)
	s_nop 0
	v_mfma_f32_32x32x16_bf16 v[48:63], v[6:9], v[10:13], v[48:63]
	ds_read_b64_tr_b16 v[6:7], v0 offset:14336
	ds_read_b64_tr_b16 v[8:9], v0 offset:15360
	v_add_f32_e32 v0, v3, v4
	v_add_f32_e32 v0, v5, v0
	v_add_f32_e32 v0, v14, v0
	v_add_f32_e32 v0, v15, v0
	v_add_f32_e32 v0, v17, v0
	v_add_f32_e32 v0, v18, v0
	s_waitcnt lgkmcnt(0)
	v_mfma_f32_32x32x16_bf16 v[32:47], v[6:9], v[10:13], v[32:47]
	v_add_f32_e32 v0, v19, v0
	v_add_f32_e32 v4, v2, v0

.LBB0_786:
	s_add_i32 s2, s43, 1
	s_cmp_lt_u32 s43, s95
	s_cbranch_scc1 .Latt1_w4
	s_waitcnt vmcnt(0)
	s_branch .Latt1_wd

.Latt1_wd:
	s_cmp_lg_u32 s43, s47
	s_waitcnt lgkmcnt(0)
	s_barrier
	s_cbranch_scc1 .LBB0_737
	v_xor_b32_e32 v0, 32, v241
	v_cmp_lt_i32_e32 vcc, v0, v242
	s_mov_b64 s[64:65], s[72:73]
	s_mov_b64 s[72:73], s[68:69]
	v_cndmask_b32_e32 v0, v241, v0, vcc
	v_lshlrev_b32_e32 v0, 2, v0
	ds_bpermute_b32 v0, v0, v225
	s_mov_b64 s[68:69], s[62:63]
	v_readlane_b32 s62, v255, 8
	s_mov_b64 s[4:5], 0
	v_readlane_b32 s63, v255, 9
	s_waitcnt lgkmcnt(0)
	v_add_f32_e32 v2, v225, v0
	v_mov_b32_e32 v0, v240

.LBB0_797:
	s_cmp_lt_u32 s88, s95
	s_cbranch_scc1 .Latt0_w4
	s_waitcnt vmcnt(0)
	s_branch .Latt0_wd

.Latt0_wd:
	s_add_i32 s88, s88, 1
	s_add_i32 s74, s74, 0x8000
	s_add_i32 s80, s80, 1
	s_add_i32 s90, s90, 2
	s_mov_b64 s[0:1], 0x90000
	s_cmp_lg_u32 s86, s74
	v_lshl_add_u64 v[22:23], v[22:23], 0, s[0:1]
	s_waitcnt lgkmcnt(0)
	s_barrier
	s_cbranch_scc0 .LBB0_664

.LBB0_825:
	v_subrev_u32_e32 v132, s89, v17
	v_subrev_u32_e32 v134, s89, v128
	v_cmp_neq_f32_e32 vcc, s54, v131
	v_mov_b32_e32 v135, 0
	v_add_u32_e32 v134, s74, v134
	v_cndmask_b32_e32 v133, 0, v131, vcc
	v_add_u32_e32 v132, s74, v132
	s_and_b64 vcc, exec, s[4:5]
	s_cbranch_vccnz .LBB0_833
	v_sub_f32_e32 v112, v112, v133
	v_exp_f32_e32 v135, v112
	v_sub_f32_e32 v112, v113, v133
	v_exp_f32_e32 v140, v112
	v_sub_f32_e32 v112, v114, v133
	v_exp_f32_e32 v141, v112
	v_sub_f32_e32 v112, v115, v133
	v_exp_f32_e32 v142, v112
	v_sub_f32_e32 v112, v116, v133
	v_exp_f32_e32 v143, v112
	v_sub_f32_e32 v112, v117, v133
	v_exp_f32_e32 v144, v112
	v_sub_f32_e32 v112, v118, v133
	v_exp_f32_e32 v145, v112
	v_sub_f32_e32 v112, v119, v133
	s_nop 0
	ds_read_b64_tr_b16 v[136:137], v134
	ds_read_b64_tr_b16 v[138:139], v134 offset:1024
	v_exp_f32_e32 v146, v112
	ds_read_b64_tr_b16 v[116:117], v132
	ds_read_b64_tr_b16 v[118:119], v132 offset:1024
	v_cvt_pk_bf16_f32 v112, v135, v140
	v_cvt_pk_bf16_f32 v113, v141, v142
	v_cvt_pk_bf16_f32 v114, v143, v144
	v_cvt_pk_bf16_f32 v115, v145, v146
	s_waitcnt lgkmcnt(2)
	s_nop 0
	v_mfma_f32_32x32x16_bf16 v[48:63], v[136:139], v[112:115], v[48:63]
	s_waitcnt lgkmcnt(0)
	v_mfma_f32_32x32x16_bf16 v[32:47], v[116:119], v[112:115], v[32:47]
	v_add_f32_e32 v112, 0, v135
	v_add_f32_e32 v112, v140, v112
	v_add_f32_e32 v112, v141, v112
	v_add_f32_e32 v112, v142, v112
	v_add_f32_e32 v112, v143, v112
	v_add_f32_e32 v112, v144, v112
	v_add_f32_e32 v112, v145, v112
	v_add_f32_e32 v135, v146, v112
	s_and_b64 vcc, exec, s[4:5]
	s_cbranch_vccz .LBB0_834

.LBB0_828:
	v_sub_f32_e32 v96, v96, v133
	v_exp_f32_e32 v116, v96
	v_sub_f32_e32 v96, v97, v133
	v_exp_f32_e32 v117, v96
	v_sub_f32_e32 v96, v98, v133
	v_exp_f32_e32 v118, v96
	v_sub_f32_e32 v96, v99, v133
	v_exp_f32_e32 v119, v96
	v_sub_f32_e32 v96, v100, v133
	v_exp_f32_e32 v120, v96
	v_sub_f32_e32 v96, v101, v133
	v_exp_f32_e32 v121, v96
	v_sub_f32_e32 v96, v102, v133
	v_exp_f32_e32 v122, v96
	v_sub_f32_e32 v96, v103, v133
	s_nop 0
	ds_read_b64_tr_b16 v[112:113], v134 offset:4096
	ds_read_b64_tr_b16 v[114:115], v134 offset:5120
	v_exp_f32_e32 v123, v96
	ds_read_b64_tr_b16 v[100:101], v132 offset:4096
	ds_read_b64_tr_b16 v[102:103], v132 offset:5120
	v_cvt_pk_bf16_f32 v96, v116, v117
	v_cvt_pk_bf16_f32 v97, v118, v119
	v_cvt_pk_bf16_f32 v98, v120, v121
	v_cvt_pk_bf16_f32 v99, v122, v123
	s_waitcnt lgkmcnt(2)
	s_nop 0
	v_mfma_f32_32x32x16_bf16 v[48:63], v[112:115], v[96:99], v[48:63]
	s_waitcnt lgkmcnt(0)
	v_mfma_f32_32x32x16_bf16 v[32:47], v[100:103], v[96:99], v[32:47]
	v_add_f32_e32 v96, v116, v135
	v_add_f32_e32 v96, v117, v96
	v_add_f32_e32 v96, v118, v96
	v_add_f32_e32 v96, v119, v96
	v_add_f32_e32 v96, v120, v96
	v_add_f32_e32 v96, v121, v96
	v_add_f32_e32 v96, v122, v96
	v_add_f32_e32 v135, v123, v96
	s_and_b64 vcc, exec, s[4:5]
	s_cbranch_vccz .LBB0_836

.LBB0_830:
	v_sub_f32_e32 v64, v64, v133
	v_exp_f32_e32 v100, v64
	v_sub_f32_e32 v64, v65, v133
	v_exp_f32_e32 v101, v64
	v_sub_f32_e32 v64, v66, v133
	v_exp_f32_e32 v102, v64
	v_sub_f32_e32 v64, v67, v133
	v_exp_f32_e32 v103, v64
	v_sub_f32_e32 v64, v68, v133
	v_exp_f32_e32 v104, v64
	v_sub_f32_e32 v64, v69, v133
	v_exp_f32_e32 v105, v64
	v_sub_f32_e32 v64, v70, v133
	v_exp_f32_e32 v106, v64
	v_sub_f32_e32 v64, v71, v133
	s_nop 0
	ds_read_b64_tr_b16 v[96:97], v134 offset:8192
	ds_read_b64_tr_b16 v[98:99], v134 offset:9216
	v_exp_f32_e32 v107, v64
	ds_read_b64_tr_b16 v[68:69], v132 offset:8192
	ds_read_b64_tr_b16 v[70:71], v132 offset:9216
	v_cvt_pk_bf16_f32 v64, v100, v101
	v_cvt_pk_bf16_f32 v65, v102, v103
	v_cvt_pk_bf16_f32 v66, v104, v105
	v_cvt_pk_bf16_f32 v67, v106, v107
	s_waitcnt lgkmcnt(2)
	s_nop 0
	v_mfma_f32_32x32x16_bf16 v[48:63], v[96:99], v[64:67], v[48:63]
	s_waitcnt lgkmcnt(0)
	v_mfma_f32_32x32x16_bf16 v[32:47], v[68:71], v[64:67], v[32:47]
	v_add_f32_e32 v64, v100, v135
	v_add_f32_e32 v64, v101, v64
	v_add_f32_e32 v64, v102, v64
	v_add_f32_e32 v64, v103, v64
	v_add_f32_e32 v64, v104, v64
	v_add_f32_e32 v64, v105, v64
	v_add_f32_e32 v64, v106, v64
	v_add_f32_e32 v135, v107, v64
	s_and_b64 vcc, exec, s[0:1]
	s_cbranch_vccz .LBB0_838

.LBB0_832:
	v_sub_f32_e32 v68, v80, v133
	v_exp_f32_e32 v72, v68
	v_sub_f32_e32 v68, v81, v133
	v_exp_f32_e32 v73, v68
	v_sub_f32_e32 v68, v82, v133
	v_exp_f32_e32 v74, v68
	v_sub_f32_e32 v68, v83, v133
	v_exp_f32_e32 v75, v68
	v_sub_f32_e32 v68, v84, v133
	v_exp_f32_e32 v76, v68
	v_sub_f32_e32 v68, v85, v133
	v_exp_f32_e32 v77, v68
	v_sub_f32_e32 v68, v86, v133
	v_exp_f32_e32 v78, v68
	v_sub_f32_e32 v68, v87, v133
	s_nop 0
	ds_read_b64_tr_b16 v[64:65], v134 offset:12288
	ds_read_b64_tr_b16 v[66:67], v134 offset:13312
	v_exp_f32_e32 v79, v68
	v_cvt_pk_bf16_f32 v68, v72, v73
	v_cvt_pk_bf16_f32 v69, v74, v75
	v_cvt_pk_bf16_f32 v70, v76, v77
	v_cvt_pk_bf16_f32 v71, v78, v79
	s_waitcnt lgkmcnt(0)
	s_nop 0
	v_mfma_f32_32x32x16_bf16 v[48:63], v[64:67], v[68:71], v[48:63]
	ds_read_b64_tr_b16 v[64:65], v132 offset:12288
	ds_read_b64_tr_b16 v[66:67], v132 offset:13312
	s_waitcnt lgkmcnt(0)
	v_mfma_f32_32x32x16_bf16 v[32:47], v[64:67], v[68:71], v[32:47]
	v_add_f32_e32 v64, v72, v135
	v_add_f32_e32 v64, v73, v64
	v_add_f32_e32 v64, v74, v64
	v_add_f32_e32 v64, v75, v64
	v_add_f32_e32 v64, v76, v64
	v_add_f32_e32 v64, v77, v64
	v_add_f32_e32 v64, v78, v64
	v_add_f32_e32 v135, v79, v64
	s_and_b64 vcc, exec, s[0:1]
	s_cbranch_vccnz .LBB0_796
	s_branch .LBB0_840

.LBB0_834:
	v_sub_f32_e32 v116, v120, v133
	v_exp_f32_e32 v120, v116
	v_sub_f32_e32 v116, v121, v133
	v_exp_f32_e32 v121, v116
	v_sub_f32_e32 v116, v122, v133
	v_exp_f32_e32 v122, v116
	v_sub_f32_e32 v116, v123, v133
	v_exp_f32_e32 v123, v116
	v_sub_f32_e32 v116, v124, v133
	v_exp_f32_e32 v124, v116
	v_sub_f32_e32 v116, v125, v133
	v_exp_f32_e32 v125, v116
	v_sub_f32_e32 v116, v126, v133
	v_exp_f32_e32 v126, v116
	v_sub_f32_e32 v116, v127, v133
	s_nop 0
	ds_read_b64_tr_b16 v[112:113], v134 offset:2048
	ds_read_b64_tr_b16 v[114:115], v134 offset:3072
	v_exp_f32_e32 v127, v116
	v_cvt_pk_bf16_f32 v116, v120, v121
	v_cvt_pk_bf16_f32 v117, v122, v123
	v_cvt_pk_bf16_f32 v118, v124, v125
	v_cvt_pk_bf16_f32 v119, v126, v127
	s_waitcnt lgkmcnt(0)
	s_nop 0
	v_mfma_f32_32x32x16_bf16 v[48:63], v[112:115], v[116:119], v[48:63]
	ds_read_b64_tr_b16 v[112:113], v132 offset:2048
	ds_read_b64_tr_b16 v[114:115], v132 offset:3072
	s_waitcnt lgkmcnt(0)
	v_mfma_f32_32x32x16_bf16 v[32:47], v[112:115], v[116:119], v[32:47]
	v_add_f32_e32 v112, v120, v135
	v_add_f32_e32 v112, v121, v112
	v_add_f32_e32 v112, v122, v112
	v_add_f32_e32 v112, v123, v112
	v_add_f32_e32 v112, v124, v112
	v_add_f32_e32 v112, v125, v112
	v_add_f32_e32 v112, v126, v112
	v_add_f32_e32 v135, v127, v112
	s_and_b64 vcc, exec, s[4:5]
	s_cbranch_vccz .LBB0_828

.LBB0_836:
	v_sub_f32_e32 v100, v104, v133
	v_exp_f32_e32 v104, v100
	v_sub_f32_e32 v100, v105, v133
	v_exp_f32_e32 v105, v100
	v_sub_f32_e32 v100, v106, v133
	v_exp_f32_e32 v106, v100
	v_sub_f32_e32 v100, v107, v133
	v_exp_f32_e32 v107, v100
	v_sub_f32_e32 v100, v108, v133
	v_exp_f32_e32 v108, v100
	v_sub_f32_e32 v100, v109, v133
	v_exp_f32_e32 v109, v100
	v_sub_f32_e32 v100, v110, v133
	v_exp_f32_e32 v110, v100
	v_sub_f32_e32 v100, v111, v133
	s_nop 0
	ds_read_b64_tr_b16 v[96:97], v134 offset:6144
	ds_read_b64_tr_b16 v[98:99], v134 offset:7168
	v_exp_f32_e32 v111, v100
	v_cvt_pk_bf16_f32 v100, v104, v105
	v_cvt_pk_bf16_f32 v101, v106, v107
	v_cvt_pk_bf16_f32 v102, v108, v109
	v_cvt_pk_bf16_f32 v103, v110, v111
	s_waitcnt lgkmcnt(0)
	s_nop 0
	v_mfma_f32_32x32x16_bf16 v[48:63], v[96:99], v[100:103], v[48:63]
	ds_read_b64_tr_b16 v[96:97], v132 offset:6144
	ds_read_b64_tr_b16 v[98:99], v132 offset:7168
	s_waitcnt lgkmcnt(0)
	v_mfma_f32_32x32x16_bf16 v[32:47], v[96:99], v[100:103], v[32:47]
	v_add_f32_e32 v96, v104, v135
	v_add_f32_e32 v96, v105, v96
	v_add_f32_e32 v96, v106, v96
	v_add_f32_e32 v96, v107, v96
	v_add_f32_e32 v96, v108, v96
	v_add_f32_e32 v96, v109, v96
	v_add_f32_e32 v96, v110, v96
	v_add_f32_e32 v135, v111, v96
	s_and_b64 vcc, exec, s[0:1]
	s_cbranch_vccz .LBB0_830

.LBB0_838:
	v_sub_f32_e32 v68, v72, v133
	v_exp_f32_e32 v72, v68
	v_sub_f32_e32 v68, v73, v133
	v_exp_f32_e32 v73, v68
	v_sub_f32_e32 v68, v74, v133
	v_exp_f32_e32 v74, v68
	v_sub_f32_e32 v68, v75, v133
	v_exp_f32_e32 v75, v68
	v_sub_f32_e32 v68, v76, v133
	v_exp_f32_e32 v76, v68
	v_sub_f32_e32 v68, v77, v133
	v_exp_f32_e32 v77, v68
	v_sub_f32_e32 v68, v78, v133
	v_exp_f32_e32 v78, v68
	v_sub_f32_e32 v68, v79, v133
	s_nop 0
	ds_read_b64_tr_b16 v[64:65], v134 offset:10240
	ds_read_b64_tr_b16 v[66:67], v134 offset:11264
	v_exp_f32_e32 v79, v68
	v_cvt_pk_bf16_f32 v68, v72, v73
	v_cvt_pk_bf16_f32 v69, v74, v75
	v_cvt_pk_bf16_f32 v70, v76, v77
	v_cvt_pk_bf16_f32 v71, v78, v79
	s_waitcnt lgkmcnt(0)
	s_nop 0
	v_mfma_f32_32x32x16_bf16 v[48:63], v[64:67], v[68:71], v[48:63]
	ds_read_b64_tr_b16 v[64:65], v132 offset:10240
	ds_read_b64_tr_b16 v[66:67], v132 offset:11264
	s_waitcnt lgkmcnt(0)
	v_mfma_f32_32x32x16_bf16 v[32:47], v[64:67], v[68:71], v[32:47]
	v_add_f32_e32 v64, v72, v135
	v_add_f32_e32 v64, v73, v64
	v_add_f32_e32 v64, v74, v64
	v_add_f32_e32 v64, v75, v64
	v_add_f32_e32 v64, v76, v64
	v_add_f32_e32 v64, v77, v64
	v_add_f32_e32 v64, v78, v64
	v_add_f32_e32 v135, v79, v64
	s_and_b64 vcc, exec, s[0:1]
	s_cbranch_vccz .LBB0_832

.LBB0_840:
	v_sub_f32_e32 v68, v88, v133
	v_exp_f32_e32 v72, v68
	v_sub_f32_e32 v68, v89, v133
	v_exp_f32_e32 v73, v68
	v_sub_f32_e32 v68, v90, v133
	v_exp_f32_e32 v74, v68
	v_sub_f32_e32 v68, v91, v133
	v_exp_f32_e32 v75, v68
	v_sub_f32_e32 v68, v92, v133
	v_exp_f32_e32 v76, v68
	v_sub_f32_e32 v68, v93, v133
	v_exp_f32_e32 v77, v68
	v_sub_f32_e32 v68, v94, v133
	v_exp_f32_e32 v78, v68
	v_sub_f32_e32 v68, v95, v133
	s_nop 0
	ds_read_b64_tr_b16 v[64:65], v134 offset:14336
	ds_read_b64_tr_b16 v[66:67], v134 offset:15360
	v_exp_f32_e32 v79, v68
	v_cvt_pk_bf16_f32 v68, v72, v73
	v_cvt_pk_bf16_f32 v69, v74, v75
	v_cvt_pk_bf16_f32 v70, v76, v77
	v_cvt_pk_bf16_f32 v71, v78, v79
	s_waitcnt lgkmcnt(0)
	s_nop 0
	v_mfma_f32_32x32x16_bf16 v[48:63], v[64:67], v[68:71], v[48:63]
	ds_read_b64_tr_b16 v[64:65], v132 offset:14336
	ds_read_b64_tr_b16 v[66:67], v132 offset:15360
	s_waitcnt lgkmcnt(0)
	v_mfma_f32_32x32x16_bf16 v[32:47], v[64:67], v[68:71], v[32:47]
	v_add_f32_e32 v64, v72, v135
	v_add_f32_e32 v64, v73, v64
	v_add_f32_e32 v64, v74, v64
	v_add_f32_e32 v64, v75, v64
	v_add_f32_e32 v64, v76, v64
	v_add_f32_e32 v64, v77, v64
	v_add_f32_e32 v64, v78, v64
	v_add_f32_e32 v135, v79, v64
	s_branch .LBB0_796
